# baseline (speedup 1.0000x reference)
; #define PG8_STAGE(bufoff, gbase, voff) do { _Pragma("unroll") for (int _i = 0; _i < 2; ++_i) \
;         __builtin_amdgcn_global_load_lds((const unsigned*)((const char*)(gbase) + (voff)[_i]), (PG8_LAS unsigned*)(lds + (bufoff) + ldsw + _i * 8192), 16, 0, 0); } while (0)
; #define PG8_LDA(dst, b, h) do { _Pragma("unroll") for (int m = 0; m < 4; ++m) _Pragma("unroll") for (int k = 0; k < 2; ++k) dst[m][k] = *(const PG8_LAS bf16x8*)(lds + PG8_SA(b, h) + aoff + m * 2048 + k * 1024); } while (0)
; #define PG8_LDB(dst, b, h) do { _Pragma("unroll") for (int n = 0; n < 2; ++n) _Pragma("unroll") for (int k = 0; k < 2; ++k) dst[n][k] = *(const PG8_LAS bf16x8*)(lds + PG8_SB(b, h) + boff + n * 2048 + k * 1024); } while (0)
; #define PG8_MMA(ai, bj, At, Bt) do { __builtin_amdgcn_s_setprio(1); _Pragma("unroll") for (int m = 0; m < 4; ++m) _Pragma("unroll") for (int n = 0; n < 2; ++n) _Pragma("unroll") for (int k = 0; k < 2; ++k) \
;         acc[ai][bj][m][n] = __builtin_amdgcn_mfma_f32_16x16x32_bf16(Bt[n][k], At[m][k], acc[ai][bj][m][n], 0, 0, 0); __builtin_amdgcn_s_setprio(0); } while (0)
; #define PG8_WAIT_V(n) asm volatile("s_waitcnt vmcnt(" #n ")" ::: "memory")
; #define PG8_WAIT_L(n) asm volatile("s_waitcnt lgkmcnt(" #n ")" ::: "memory")
; template <class Epi, class Sched, bool ALIGN_EPI = false, bool SP2 = false>
; __device__ __forceinline__ void gemm_phase(PG8_LAS unsigned char* lds, const Gemm g, const Sched& S, const Epi& E, int wid_s_) {
;     ...
;             const bool last = (t == nt - 2);
;             const char* a1 = cA + (size_t)(t + 1) * kstep;
;             const char* a2 = last ? nA : cA + (size_t)(t + 2) * kstep; const char* b2 = last ? nB : cB + (size_t)(t + 2) * kstep;
;             const char* a3 = a2 + kstep; const char* b3 = b2 + kstep;
;             if (last && has_next) S.a_ready(nxt);
;             if constexpr (SP2) {
;             PG8_LDB(B0, 0, 0); PG8_LDB(B1, 0, 1); PG8_SCHED; PG8_LDA(At, 0, 0); PG8_STAGE(PG8_SA(1, 1), a1 + hstep, voffA);
;             PG8_WAIT_V(8); PG8_WAIT_L(0); PG8_BAR; PG8_MMA(0, 0, At, B0); PG8_MMA(0, 1, At, B1); PG8_BAR; PG8_SCHED;
;             PG8_LDA(At, 0, 1); PG8_STAGE(PG8_SB(0, 0), b2, voffB); PG8_STAGE(PG8_SB(0, 1), b2 + hstep, voffB); PG8_STAGE(PG8_SA(0, 0), a2, voffA);
;             PG8_WAIT_V(8); PG8_WAIT_L(0); PG8_BAR; PG8_MMA(1, 0, At, B0); PG8_MMA(1, 1, At, B1); PG8_BAR; PG8_SCHED;
.LBB0_384:
	s_add_i32 vcc_lo, s48, 2
	s_add_u32 s78, s24, 0x80
	s_addc_u32 s49, s25, 0
	s_add_i32 vcc_hi, 16, 0x10000
	s_cmp_eq_u32 s87, s48
	s_cselect_b32 s49, s3, s49
	s_cselect_b32 s48, s2, s78
	v_add_u32_e32 v96, vcc_hi, v147
	s_cselect_b32 s79, s23, s81
	s_cselect_b32 s78, s22, s80
	s_add_i32 s40, 16, 0x14000
	ds_read_b128 v[130:133], v96
	ds_read_b128 v[134:137], v96 offset:1024
	ds_read_b128 v[138:141], v96 offset:2048
	ds_read_b128 v[142:145], v96 offset:3072
	v_add_u32_e32 v96, s40, v147
	ds_read_b128 v[168:171], v96
	ds_read_b128 v[172:175], v96 offset:1024
	ds_read_b128 v[176:179], v96 offset:2048
	ds_read_b128 v[180:183], v96 offset:3072
	s_add_i32 m0, s51, 0xc000
	ds_read_b128 v[194:197], v148
	ds_read_b128 v[198:201], v148 offset:1024
	ds_read_b128 v[202:205], v148 offset:2048
	ds_read_b128 v[206:209], v148 offset:3072
	ds_read_b128 v[210:213], v148 offset:4096
	ds_read_b128 v[214:217], v148 offset:5120
	ds_read_b128 v[218:221], v148 offset:6144
	ds_read_b128 v[222:225], v148 offset:7168
	global_load_lds_dwordx4 v166, s[24:25]
	s_add_i32 m0, s51, 0xe000
	s_nop 0
	global_load_lds_dwordx4 v164, s[24:25]
	s_waitcnt vmcnt(8)
	s_waitcnt lgkmcnt(0)
	s_barrier
	s_setprio 1
	s_waitcnt lgkmcnt(0)
	v_mfma_f32_16x16x32_bf16 v[122:125], v[130:133], v[194:197], v[122:125]
	v_mfma_f32_16x16x32_bf16 v[118:121], v[138:141], v[194:197], v[118:121]
	v_mfma_f32_16x16x32_bf16 v[92:95], v[130:133], v[202:205], v[92:95]
	v_mfma_f32_16x16x32_bf16 v[84:87], v[138:141], v[202:205], v[84:87]
	v_mfma_f32_16x16x32_bf16 v[60:63], v[130:133], v[210:213], v[60:63]
	v_mfma_f32_16x16x32_bf16 v[52:55], v[138:141], v[210:213], v[52:55]
	v_mfma_f32_16x16x32_bf16 v[28:31], v[130:133], v[218:221], v[28:31]
	v_mfma_f32_16x16x32_bf16 v[20:23], v[138:141], v[218:221], v[20:23]
	v_mfma_f32_16x16x32_bf16 v[122:125], v[134:137], v[198:201], v[122:125]
	v_mfma_f32_16x16x32_bf16 v[118:121], v[142:145], v[198:201], v[118:121]
	v_mfma_f32_16x16x32_bf16 v[92:95], v[134:137], v[206:209], v[92:95]
	v_mfma_f32_16x16x32_bf16 v[84:87], v[142:145], v[206:209], v[84:87]
	v_mfma_f32_16x16x32_bf16 v[60:63], v[134:137], v[214:217], v[60:63]
	v_mfma_f32_16x16x32_bf16 v[52:55], v[142:145], v[214:217], v[52:55]
	v_mfma_f32_16x16x32_bf16 v[28:31], v[134:137], v[222:225], v[28:31]
	v_mfma_f32_16x16x32_bf16 v[20:23], v[142:145], v[222:225], v[20:23]
	v_mfma_f32_16x16x32_bf16 v[110:113], v[168:171], v[194:197], v[110:113]
	v_mfma_f32_16x16x32_bf16 v[102:105], v[176:179], v[194:197], v[102:105]
	v_mfma_f32_16x16x32_bf16 v[76:79], v[168:171], v[202:205], v[76:79]
	v_mfma_f32_16x16x32_bf16 v[68:71], v[176:179], v[202:205], v[68:71]
	v_mfma_f32_16x16x32_bf16 v[44:47], v[168:171], v[210:213], v[44:47]
	v_mfma_f32_16x16x32_bf16 v[36:39], v[176:179], v[210:213], v[36:39]
	v_mfma_f32_16x16x32_bf16 v[12:15], v[168:171], v[218:221], v[12:15]
	v_mfma_f32_16x16x32_bf16 v[4:7], v[176:179], v[218:221], v[4:7]
	v_mfma_f32_16x16x32_bf16 v[110:113], v[172:175], v[198:201], v[110:113]
	v_mfma_f32_16x16x32_bf16 v[102:105], v[180:183], v[198:201], v[102:105]
	v_mfma_f32_16x16x32_bf16 v[76:79], v[172:175], v[206:209], v[76:79]
	v_mfma_f32_16x16x32_bf16 v[68:71], v[180:183], v[206:209], v[68:71]
	v_mfma_f32_16x16x32_bf16 v[44:47], v[172:175], v[214:217], v[44:47]
	v_mfma_f32_16x16x32_bf16 v[36:39], v[180:183], v[214:217], v[36:39]
	v_mfma_f32_16x16x32_bf16 v[12:15], v[172:175], v[222:225], v[12:15]
	v_mfma_f32_16x16x32_bf16 v[4:7], v[180:183], v[222:225], v[4:7]
	s_setprio 0
	s_barrier
	s_add_i32 vcc_hi, vcc_hi, s50
	s_mov_b32 m0, vcc_hi
	ds_read_b128 v[194:197], v148 offset:16384
	ds_read_b128 v[198:201], v148 offset:17408
	ds_read_b128 v[202:205], v148 offset:18432
	ds_read_b128 v[206:209], v148 offset:19456
	ds_read_b128 v[210:213], v148 offset:20480
	ds_read_b128 v[214:217], v148 offset:21504
	ds_read_b128 v[218:221], v148 offset:22528
	ds_read_b128 v[222:225], v148 offset:23552
	global_load_lds_dwordx4 v154, s[78:79]
	s_add_i32 m0, vcc_hi, 0x2000
	s_add_i32 s40, s40, s50
	global_load_lds_dwordx4 v158, s[78:79]
	s_mov_b32 m0, s40
	s_nop 0
	global_load_lds_dwordx4 v150, s[78:79]
	s_add_i32 m0, s40, 0x2000
	s_nop 0
	global_load_lds_dwordx4 v151, s[78:79]
	s_mov_b32 m0, s51
	s_nop 0
	global_load_lds_dwordx4 v152, s[48:49]
	s_mov_b32 m0, s82
	s_nop 0
	global_load_lds_dwordx4 v156, s[48:49]
	s_waitcnt vmcnt(8)
	s_waitcnt lgkmcnt(0)
	s_barrier
	s_setprio 1
	s_waitcnt lgkmcnt(0)
	v_mfma_f32_16x16x32_bf16 v[126:129], v[130:133], v[194:197], v[126:129]
	v_mfma_f32_16x16x32_bf16 v[114:117], v[138:141], v[194:197], v[114:117]
	v_mfma_f32_16x16x32_bf16 v[88:91], v[130:133], v[202:205], v[88:91]
	v_mfma_f32_16x16x32_bf16 v[80:83], v[138:141], v[202:205], v[80:83]
	v_mfma_f32_16x16x32_bf16 v[56:59], v[130:133], v[210:213], v[56:59]
	v_mfma_f32_16x16x32_bf16 v[48:51], v[138:141], v[210:213], v[48:51]
	v_mfma_f32_16x16x32_bf16 v[24:27], v[130:133], v[218:221], v[24:27]
	v_mfma_f32_16x16x32_bf16 v[16:19], v[138:141], v[218:221], v[16:19]
	v_mfma_f32_16x16x32_bf16 v[126:129], v[134:137], v[198:201], v[126:129]
	v_mfma_f32_16x16x32_bf16 v[114:117], v[142:145], v[198:201], v[114:117]
	v_mfma_f32_16x16x32_bf16 v[88:91], v[134:137], v[206:209], v[88:91]
	v_mfma_f32_16x16x32_bf16 v[80:83], v[142:145], v[206:209], v[80:83]
	v_mfma_f32_16x16x32_bf16 v[56:59], v[134:137], v[214:217], v[56:59]
	v_mfma_f32_16x16x32_bf16 v[48:51], v[142:145], v[214:217], v[48:51]
	v_mfma_f32_16x16x32_bf16 v[24:27], v[134:137], v[222:225], v[24:27]
	v_mfma_f32_16x16x32_bf16 v[16:19], v[142:145], v[222:225], v[16:19]
	v_mfma_f32_16x16x32_bf16 v[106:109], v[168:171], v[194:197], v[106:109]
	v_mfma_f32_16x16x32_bf16 v[98:101], v[176:179], v[194:197], v[98:101]
	v_mfma_f32_16x16x32_bf16 v[72:75], v[168:171], v[202:205], v[72:75]
	v_mfma_f32_16x16x32_bf16 v[64:67], v[176:179], v[202:205], v[64:67]
	v_mfma_f32_16x16x32_bf16 v[40:43], v[168:171], v[210:213], v[40:43]
	v_mfma_f32_16x16x32_bf16 v[32:35], v[176:179], v[210:213], v[32:35]
	v_mfma_f32_16x16x32_bf16 v[8:11], v[168:171], v[218:221], v[8:11]
	v_mfma_f32_16x16x32_bf16 v[0:3], v[176:179], v[218:221], v[0:3]
	v_mfma_f32_16x16x32_bf16 v[106:109], v[172:175], v[198:201], v[106:109]
	v_mfma_f32_16x16x32_bf16 v[98:101], v[180:183], v[198:201], v[98:101]
	v_mfma_f32_16x16x32_bf16 v[72:75], v[172:175], v[206:209], v[72:75]
	v_mfma_f32_16x16x32_bf16 v[64:67], v[180:183], v[206:209], v[64:67]
	v_mfma_f32_16x16x32_bf16 v[40:43], v[172:175], v[214:217], v[40:43]
	v_mfma_f32_16x16x32_bf16 v[32:35], v[180:183], v[214:217], v[32:35]
	v_mfma_f32_16x16x32_bf16 v[8:11], v[172:175], v[222:225], v[8:11]
	v_mfma_f32_16x16x32_bf16 v[0:3], v[180:183], v[222:225], v[0:3]
	s_setprio 0
	s_barrier
; #define PG8_STAGE(bufoff, gbase, voff) do { _Pragma("unroll") for (int _i = 0; _i < 2; ++_i) \
;         __builtin_amdgcn_global_load_lds((const unsigned*)((const char*)(gbase) + (voff)[_i]), (PG8_LAS unsigned*)(lds + (bufoff) + ldsw + _i * 8192), 16, 0, 0); } while (0)
; #define PG8_LDA(dst, b, h) do { _Pragma("unroll") for (int m = 0; m < 4; ++m) _Pragma("unroll") for (int k = 0; k < 2; ++k) dst[m][k] = *(const PG8_LAS bf16x8*)(lds + PG8_SA(b, h) + aoff + m * 2048 + k * 1024); } while (0)
; #define PG8_WAIT_V(n) asm volatile("s_waitcnt vmcnt(" #n ")" ::: "memory")
; #define PG8_WAIT_L(n) asm volatile("s_waitcnt lgkmcnt(" #n ")" ::: "memory")
; #define PG8_BAR __builtin_amdgcn_s_barrier()
; template <class Epi, class Sched, bool ALIGN_EPI = false, bool SP2 = false>
; __device__ __forceinline__ void gemm_phase(PG8_LAS unsigned char* lds, const Gemm g, const Sched& S, const Epi& E, int wid_s_) {
;     ...
;         for (int t = 0; t < nt; t += 2) {
;             const bool last = (t == nt - 2);
;             const char* a1 = cA + (size_t)(t + 1) * kstep;
;             const char* a2 = last ? nA : cA + (size_t)(t + 2) * kstep; const char* b2 = last ? nB : cB + (size_t)(t + 2) * kstep;
;             const char* a3 = a2 + kstep; const char* b3 = b2 + kstep;
;             if (last && has_next) S.a_ready(nxt);
;             if constexpr (SP2) {
;             PG8_LDB(B0, 0, 0); PG8_LDB(B1, 0, 1); PG8_SCHED; PG8_LDA(At, 0, 0); PG8_STAGE(PG8_SA(1, 1), a1 + hstep, voffA);
;             PG8_WAIT_V(8); PG8_WAIT_L(0); PG8_BAR; PG8_MMA(0, 0, At, B0); PG8_MMA(0, 1, At, B1); PG8_BAR; PG8_SCHED;
;             PG8_LDA(At, 0, 1); PG8_STAGE(PG8_SB(0, 0), b2, voffB); PG8_STAGE(PG8_SB(0, 1), b2 + hstep, voffB); PG8_STAGE(PG8_SA(0, 0), a2, voffA);
;             PG8_WAIT_V(8); PG8_WAIT_L(0); PG8_BAR; PG8_MMA(1, 0, At, B0); PG8_MMA(1, 1, At, B1); PG8_BAR; PG8_SCHED;
;             PG8_LDB(B0, 1, 0); PG8_LDB(B1, 1, 1); PG8_SCHED; PG8_LDA(At, 1, 0); PG8_STAGE(PG8_SA(0, 1), a2 + hstep, voffA);
;             PG8_WAIT_V(8); PG8_WAIT_L(0); PG8_BAR; PG8_MMA(0, 0, At, B0); PG8_MMA(0, 1, At, B1); PG8_BAR; PG8_SCHED;
;             PG8_LDA(At, 1, 1); PG8_STAGE(PG8_SB(1, 0), b3, voffB); PG8_STAGE(PG8_SB(1, 1), b3 + hstep, voffB); PG8_STAGE(PG8_SA(1, 0), a3, voffA);
;             PG8_WAIT_V(8); PG8_WAIT_L(0); PG8_BAR; PG8_MMA(1, 0, At, B0); PG8_MMA(1, 1, At, B1); PG8_BAR; PG8_SCHED;
	s_add_i32 s40, 16, 0x18000
	v_add_u32_e32 v96, s40, v147
	ds_read_b128 v[130:133], v96
	ds_read_b128 v[134:137], v96 offset:1024
	ds_read_b128 v[138:141], v96 offset:2048
	ds_read_b128 v[142:145], v96 offset:3072
	v_add_u32_e32 v96, 0x1c010, v147
	ds_read_b128 v[168:171], v96
	ds_read_b128 v[172:175], v96 offset:1024
	ds_read_b128 v[176:179], v96 offset:2048
	ds_read_b128 v[180:183], v96 offset:3072
	s_mov_b32 m0, s83
	ds_read_b128 v[194:197], v148 offset:32768
	ds_read_b128 v[198:201], v148 offset:33792
	ds_read_b128 v[202:205], v148 offset:34816
	ds_read_b128 v[206:209], v148 offset:35840
	ds_read_b128 v[210:213], v148 offset:36864
	ds_read_b128 v[214:217], v148 offset:37888
	ds_read_b128 v[218:221], v148 offset:38912
	ds_read_b128 v[222:225], v148 offset:39936
	global_load_lds_dwordx4 v188, s[48:49]
	s_mov_b32 m0, s84
	s_nop 0
	global_load_lds_dwordx4 v189, s[48:49]
	s_waitcnt vmcnt(8)
	s_waitcnt lgkmcnt(0)
	s_barrier
	s_setprio 1
	s_waitcnt lgkmcnt(0)
	v_mfma_f32_16x16x32_bf16 v[122:125], v[130:133], v[194:197], v[122:125]
	v_mfma_f32_16x16x32_bf16 v[118:121], v[138:141], v[194:197], v[118:121]
	v_mfma_f32_16x16x32_bf16 v[92:95], v[130:133], v[202:205], v[92:95]
	v_mfma_f32_16x16x32_bf16 v[84:87], v[138:141], v[202:205], v[84:87]
	v_mfma_f32_16x16x32_bf16 v[60:63], v[130:133], v[210:213], v[60:63]
	v_mfma_f32_16x16x32_bf16 v[52:55], v[138:141], v[210:213], v[52:55]
	v_mfma_f32_16x16x32_bf16 v[28:31], v[130:133], v[218:221], v[28:31]
	v_mfma_f32_16x16x32_bf16 v[20:23], v[138:141], v[218:221], v[20:23]
	v_mfma_f32_16x16x32_bf16 v[122:125], v[134:137], v[198:201], v[122:125]
	v_mfma_f32_16x16x32_bf16 v[118:121], v[142:145], v[198:201], v[118:121]
	v_mfma_f32_16x16x32_bf16 v[92:95], v[134:137], v[206:209], v[92:95]
	v_mfma_f32_16x16x32_bf16 v[84:87], v[142:145], v[206:209], v[84:87]
	v_mfma_f32_16x16x32_bf16 v[60:63], v[134:137], v[214:217], v[60:63]
	v_mfma_f32_16x16x32_bf16 v[52:55], v[142:145], v[214:217], v[52:55]
	v_mfma_f32_16x16x32_bf16 v[28:31], v[134:137], v[222:225], v[28:31]
	v_mfma_f32_16x16x32_bf16 v[20:23], v[142:145], v[222:225], v[20:23]
	v_mfma_f32_16x16x32_bf16 v[110:113], v[168:171], v[194:197], v[110:113]
	v_mfma_f32_16x16x32_bf16 v[102:105], v[176:179], v[194:197], v[102:105]
	v_mfma_f32_16x16x32_bf16 v[76:79], v[168:171], v[202:205], v[76:79]
	v_mfma_f32_16x16x32_bf16 v[68:71], v[176:179], v[202:205], v[68:71]
	v_mfma_f32_16x16x32_bf16 v[44:47], v[168:171], v[210:213], v[44:47]
	v_mfma_f32_16x16x32_bf16 v[36:39], v[176:179], v[210:213], v[36:39]
	v_mfma_f32_16x16x32_bf16 v[12:15], v[168:171], v[218:221], v[12:15]
	v_mfma_f32_16x16x32_bf16 v[4:7], v[176:179], v[218:221], v[4:7]
	v_mfma_f32_16x16x32_bf16 v[110:113], v[172:175], v[198:201], v[110:113]
	v_mfma_f32_16x16x32_bf16 v[102:105], v[180:183], v[198:201], v[102:105]
	v_mfma_f32_16x16x32_bf16 v[76:79], v[172:175], v[206:209], v[76:79]
	v_mfma_f32_16x16x32_bf16 v[68:71], v[180:183], v[206:209], v[68:71]
	v_mfma_f32_16x16x32_bf16 v[44:47], v[172:175], v[214:217], v[44:47]
	v_mfma_f32_16x16x32_bf16 v[36:39], v[180:183], v[214:217], v[36:39]
	v_mfma_f32_16x16x32_bf16 v[12:15], v[172:175], v[222:225], v[12:15]
	v_mfma_f32_16x16x32_bf16 v[4:7], v[180:183], v[222:225], v[4:7]
	s_setprio 0
	s_barrier
	s_add_i32 s40, s40, s50
	s_mov_b32 m0, s40
	ds_read_b128 v[194:197], v148 offset:49152
	ds_read_b128 v[198:201], v148 offset:50176
	ds_read_b128 v[202:205], v148 offset:51200
	ds_read_b128 v[206:209], v148 offset:52224
	ds_read_b128 v[210:213], v148 offset:53248
	ds_read_b128 v[214:217], v148 offset:54272
	ds_read_b128 v[218:221], v148 offset:55296
	ds_read_b128 v[222:225], v148 offset:56320
	global_load_lds_dwordx4 v192, s[78:79]
	s_add_i32 m0, s40, 0x2000
	s_add_i32 s40, s50, 0x1c010
	global_load_lds_dwordx4 v193, s[78:79]
	s_mov_b32 m0, s40
	s_nop 0
	global_load_lds_dwordx4 v226, s[78:79]
	s_add_i32 m0, s40, 0x2000
	s_nop 0
	global_load_lds_dwordx4 v227, s[78:79]
	s_mov_b32 m0, s85
	s_nop 0
	global_load_lds_dwordx4 v228, s[48:49]
	s_mov_b32 m0, s86
	s_nop 0
	global_load_lds_dwordx4 v229, s[48:49]
	s_waitcnt vmcnt(8)
	s_waitcnt lgkmcnt(0)
	s_barrier
	s_setprio 1
	s_waitcnt lgkmcnt(0)
	v_mfma_f32_16x16x32_bf16 v[126:129], v[130:133], v[194:197], v[126:129]
	v_mfma_f32_16x16x32_bf16 v[114:117], v[138:141], v[194:197], v[114:117]
	v_mfma_f32_16x16x32_bf16 v[88:91], v[130:133], v[202:205], v[88:91]
	v_mfma_f32_16x16x32_bf16 v[80:83], v[138:141], v[202:205], v[80:83]
	v_mfma_f32_16x16x32_bf16 v[56:59], v[130:133], v[210:213], v[56:59]
	v_mfma_f32_16x16x32_bf16 v[48:51], v[138:141], v[210:213], v[48:51]
	v_mfma_f32_16x16x32_bf16 v[24:27], v[130:133], v[218:221], v[24:27]
	v_mfma_f32_16x16x32_bf16 v[16:19], v[138:141], v[218:221], v[16:19]
	v_mfma_f32_16x16x32_bf16 v[126:129], v[134:137], v[198:201], v[126:129]
	v_mfma_f32_16x16x32_bf16 v[114:117], v[142:145], v[198:201], v[114:117]
	v_mfma_f32_16x16x32_bf16 v[88:91], v[134:137], v[206:209], v[88:91]
	v_mfma_f32_16x16x32_bf16 v[80:83], v[142:145], v[206:209], v[80:83]
	v_mfma_f32_16x16x32_bf16 v[56:59], v[134:137], v[214:217], v[56:59]
	v_mfma_f32_16x16x32_bf16 v[48:51], v[142:145], v[214:217], v[48:51]
	v_mfma_f32_16x16x32_bf16 v[24:27], v[134:137], v[222:225], v[24:27]
	v_mfma_f32_16x16x32_bf16 v[16:19], v[142:145], v[222:225], v[16:19]
	v_mfma_f32_16x16x32_bf16 v[106:109], v[168:171], v[194:197], v[106:109]
	v_mfma_f32_16x16x32_bf16 v[98:101], v[176:179], v[194:197], v[98:101]
	v_mfma_f32_16x16x32_bf16 v[72:75], v[168:171], v[202:205], v[72:75]
	v_mfma_f32_16x16x32_bf16 v[64:67], v[176:179], v[202:205], v[64:67]
	v_mfma_f32_16x16x32_bf16 v[40:43], v[168:171], v[210:213], v[40:43]
	v_mfma_f32_16x16x32_bf16 v[32:35], v[176:179], v[210:213], v[32:35]
	v_mfma_f32_16x16x32_bf16 v[8:11], v[168:171], v[218:221], v[8:11]
	v_mfma_f32_16x16x32_bf16 v[0:3], v[176:179], v[218:221], v[0:3]
	v_mfma_f32_16x16x32_bf16 v[106:109], v[172:175], v[198:201], v[106:109]
	v_mfma_f32_16x16x32_bf16 v[98:101], v[180:183], v[198:201], v[98:101]
	v_mfma_f32_16x16x32_bf16 v[72:75], v[172:175], v[206:209], v[72:75]
	v_mfma_f32_16x16x32_bf16 v[64:67], v[180:183], v[206:209], v[64:67]
	v_mfma_f32_16x16x32_bf16 v[40:43], v[172:175], v[214:217], v[40:43]
	v_mfma_f32_16x16x32_bf16 v[32:35], v[180:183], v[214:217], v[32:35]
	v_mfma_f32_16x16x32_bf16 v[8:11], v[172:175], v[222:225], v[8:11]
	v_mfma_f32_16x16x32_bf16 v[0:3], v[180:183], v[222:225], v[0:3]
	s_setprio 0
	s_barrier
	s_add_u32 s80, s80, 0x100
	s_addc_u32 s81, s81, 0
	s_add_u32 s24, s24, 0x100
	s_addc_u32 s25, s25, 0
	s_cmp_ge_i32 vcc_lo, s4
	s_mov_b32 s48, vcc_lo
	s_cbranch_scc0 .LBB0_384
	s_add_i32 s78, 16, 0x1c000
	s_movk_i32 s80, 0x4000
	v_add_u32_e32 v192, 64, v191

; #define PG8_STAGE(bufoff, gbase, voff) do { _Pragma("unroll") for (int _i = 0; _i < 2; ++_i) \
;         __builtin_amdgcn_global_load_lds((const unsigned*)((const char*)(gbase) + (voff)[_i]), (PG8_LAS unsigned*)(lds + (bufoff) + ldsw + _i * 8192), 16, 0, 0); } while (0)
; #define PG8_LDA(dst, b, h) do { _Pragma("unroll") for (int m = 0; m < 4; ++m) _Pragma("unroll") for (int k = 0; k < 2; ++k) dst[m][k] = *(const PG8_LAS bf16x8*)(lds + PG8_SA(b, h) + aoff + m * 2048 + k * 1024); } while (0)
; #define PG8_LDB(dst, b, h) do { _Pragma("unroll") for (int n = 0; n < 2; ++n) _Pragma("unroll") for (int k = 0; k < 2; ++k) dst[n][k] = *(const PG8_LAS bf16x8*)(lds + PG8_SB(b, h) + boff + n * 2048 + k * 1024); } while (0)
; #define PG8_MMA(ai, bj, At, Bt) do { __builtin_amdgcn_s_setprio(1); _Pragma("unroll") for (int m = 0; m < 4; ++m) _Pragma("unroll") for (int n = 0; n < 2; ++n) _Pragma("unroll") for (int k = 0; k < 2; ++k) \
;         acc[ai][bj][m][n] = __builtin_amdgcn_mfma_f32_16x16x32_bf16(Bt[n][k], At[m][k], acc[ai][bj][m][n], 0, 0, 0); __builtin_amdgcn_s_setprio(0); } while (0)
; #define PG8_WAIT_V(n) asm volatile("s_waitcnt vmcnt(" #n ")" ::: "memory")
; #define PG8_BAR __builtin_amdgcn_s_barrier()
; template <class Epi, class Sched, bool ALIGN_EPI = false, bool SP2 = false>
; __device__ __forceinline__ void gemm_phase(PG8_LAS unsigned char* lds, const Gemm g, const Sched& S, const Epi& E, int wid_s_) {
;     ...
;         for (int t = 0; t < nt; t += 2) {
;             const bool last = (t == nt - 2);
;             const char* a1 = cA + (size_t)(t + 1) * kstep;
;             const char* a2 = last ? nA : cA + (size_t)(t + 2) * kstep; const char* b2 = last ? nB : cB + (size_t)(t + 2) * kstep;
;             const char* a3 = a2 + kstep; const char* b3 = b2 + kstep;
;             if (last && has_next) S.a_ready(nxt);
;             if constexpr (SP2) {
;             PG8_LDB(B0, 0, 0); PG8_LDB(B1, 0, 1); PG8_SCHED; PG8_LDA(At, 0, 0); PG8_STAGE(PG8_SA(1, 1), a1 + hstep, voffA);
;             PG8_WAIT_V(8); PG8_WAIT_L(0); PG8_BAR; PG8_MMA(0, 0, At, B0); PG8_MMA(0, 1, At, B1); PG8_BAR; PG8_SCHED;
;             PG8_LDA(At, 0, 1); PG8_STAGE(PG8_SB(0, 0), b2, voffB); PG8_STAGE(PG8_SB(0, 1), b2 + hstep, voffB); PG8_STAGE(PG8_SA(0, 0), a2, voffA);
;             PG8_WAIT_V(8); PG8_WAIT_L(0); PG8_BAR; PG8_MMA(1, 0, At, B0); PG8_MMA(1, 1, At, B1); PG8_BAR; PG8_SCHED;
.LBB0_788:
	s_add_i32 vcc_hi, s20, 2
	s_add_u32 s8, s18, 0x80
	s_addc_u32 s9, s19, 0
	s_add_i32 s78, 16, 0x10000
	s_cmp_eq_u32 s85, s20
	s_cselect_b32 s21, s3, s9
	s_cselect_b32 s20, s2, s8
	v_add_u32_e32 v96, s78, v147
	s_cselect_b32 s9, s17, vcc_lo
	s_cselect_b32 s8, s16, s91
	s_add_i32 s79, 16, 0x14000
	ds_read_b128 v[142:145], v96
	ds_read_b128 v[150:153], v96 offset:1024
	ds_read_b128 v[154:157], v96 offset:2048
	ds_read_b128 v[158:161], v96 offset:3072
	v_add_u32_e32 v96, s79, v147
	ds_read_b128 v[162:165], v96
	ds_read_b128 v[166:169], v96 offset:1024
	ds_read_b128 v[170:173], v96 offset:2048
	ds_read_b128 v[174:177], v96 offset:3072
	s_add_i32 m0, s48, 0xc000
	ds_read_b128 v[180:183], v149
	ds_read_b128 v[196:199], v149 offset:1024
	ds_read_b128 v[200:203], v149 offset:2048
	ds_read_b128 v[204:207], v149 offset:3072
	ds_read_b128 v[208:211], v149 offset:4096
	ds_read_b128 v[212:215], v149 offset:5120
	ds_read_b128 v[216:219], v149 offset:6144
	ds_read_b128 v[220:223], v149 offset:7168
	global_load_lds_dwordx4 v140, s[18:19]
	s_add_i32 m0, s48, 0xe000
	s_nop 0
	global_load_lds_dwordx4 v138, s[18:19]
	s_waitcnt vmcnt(8)
	s_waitcnt lgkmcnt(0)
	s_barrier
	s_setprio 1
	s_waitcnt lgkmcnt(0)
	v_mfma_f32_16x16x32_bf16 v[126:129], v[142:145], v[180:183], v[126:129]
	v_mfma_f32_16x16x32_bf16 v[122:125], v[154:157], v[180:183], v[122:125]
	v_mfma_f32_16x16x32_bf16 v[118:121], v[142:145], v[200:203], v[118:121]
	v_mfma_f32_16x16x32_bf16 v[114:117], v[154:157], v[200:203], v[114:117]
	v_mfma_f32_16x16x32_bf16 v[106:109], v[142:145], v[208:211], v[106:109]
	v_mfma_f32_16x16x32_bf16 v[98:101], v[154:157], v[208:211], v[98:101]
	v_mfma_f32_16x16x32_bf16 v[88:91], v[142:145], v[216:219], v[88:91]
	v_mfma_f32_16x16x32_bf16 v[80:83], v[154:157], v[216:219], v[80:83]
	v_mfma_f32_16x16x32_bf16 v[126:129], v[150:153], v[196:199], v[126:129]
	v_mfma_f32_16x16x32_bf16 v[122:125], v[158:161], v[196:199], v[122:125]
	v_mfma_f32_16x16x32_bf16 v[118:121], v[150:153], v[204:207], v[118:121]
	v_mfma_f32_16x16x32_bf16 v[114:117], v[158:161], v[204:207], v[114:117]
	v_mfma_f32_16x16x32_bf16 v[106:109], v[150:153], v[212:215], v[106:109]
	v_mfma_f32_16x16x32_bf16 v[98:101], v[158:161], v[212:215], v[98:101]
	v_mfma_f32_16x16x32_bf16 v[88:91], v[150:153], v[220:223], v[88:91]
	v_mfma_f32_16x16x32_bf16 v[80:83], v[158:161], v[220:223], v[80:83]
	v_mfma_f32_16x16x32_bf16 v[110:113], v[162:165], v[180:183], v[110:113]
	v_mfma_f32_16x16x32_bf16 v[102:105], v[170:173], v[180:183], v[102:105]
	v_mfma_f32_16x16x32_bf16 v[92:95], v[162:165], v[200:203], v[92:95]
	v_mfma_f32_16x16x32_bf16 v[84:87], v[170:173], v[200:203], v[84:87]
	v_mfma_f32_16x16x32_bf16 v[76:79], v[162:165], v[208:211], v[76:79]
	v_mfma_f32_16x16x32_bf16 v[72:75], v[170:173], v[208:211], v[72:75]
	v_mfma_f32_16x16x32_bf16 v[68:71], v[162:165], v[216:219], v[68:71]
	v_mfma_f32_16x16x32_bf16 v[64:67], v[170:173], v[216:219], v[64:67]
	v_mfma_f32_16x16x32_bf16 v[110:113], v[166:169], v[196:199], v[110:113]
	v_mfma_f32_16x16x32_bf16 v[102:105], v[174:177], v[196:199], v[102:105]
	v_mfma_f32_16x16x32_bf16 v[92:95], v[166:169], v[204:207], v[92:95]
	v_mfma_f32_16x16x32_bf16 v[84:87], v[174:177], v[204:207], v[84:87]
	v_mfma_f32_16x16x32_bf16 v[76:79], v[166:169], v[212:215], v[76:79]
	v_mfma_f32_16x16x32_bf16 v[72:75], v[174:177], v[212:215], v[72:75]
	v_mfma_f32_16x16x32_bf16 v[68:71], v[166:169], v[220:223], v[68:71]
	v_mfma_f32_16x16x32_bf16 v[64:67], v[174:177], v[220:223], v[64:67]
	s_setprio 0
	s_barrier
	s_add_i32 s78, s78, s41
	s_mov_b32 m0, s78
	ds_read_b128 v[180:183], v149 offset:16384
	ds_read_b128 v[196:199], v149 offset:17408
	ds_read_b128 v[200:203], v149 offset:18432
	ds_read_b128 v[204:207], v149 offset:19456
	ds_read_b128 v[208:211], v149 offset:20480
	ds_read_b128 v[212:215], v149 offset:21504
	ds_read_b128 v[216:219], v149 offset:22528
	ds_read_b128 v[220:223], v149 offset:23552
	global_load_lds_dwordx4 v132, s[8:9]
	s_add_i32 m0, s78, 0x2000
	s_add_i32 s78, s79, s41
	global_load_lds_dwordx4 v136, s[8:9]
	s_mov_b32 m0, s78
	s_nop 0
	global_load_lds_dwordx4 v178, s[8:9]
	s_add_i32 m0, s78, 0x2000
	s_nop 0
	global_load_lds_dwordx4 v179, s[8:9]
	s_mov_b32 m0, s48
	s_nop 0
	global_load_lds_dwordx4 v130, s[20:21]
	s_mov_b32 m0, s49
	s_nop 0
	global_load_lds_dwordx4 v134, s[20:21]
	s_waitcnt vmcnt(8)
	s_waitcnt lgkmcnt(0)
	s_barrier
	s_setprio 1
	s_waitcnt lgkmcnt(0)
	v_mfma_f32_16x16x32_bf16 v[60:63], v[142:145], v[180:183], v[60:63]
	v_mfma_f32_16x16x32_bf16 v[56:59], v[154:157], v[180:183], v[56:59]
	v_mfma_f32_16x16x32_bf16 v[52:55], v[142:145], v[200:203], v[52:55]
	v_mfma_f32_16x16x32_bf16 v[48:51], v[154:157], v[200:203], v[48:51]
	v_mfma_f32_16x16x32_bf16 v[40:43], v[142:145], v[208:211], v[40:43]
	v_mfma_f32_16x16x32_bf16 v[32:35], v[154:157], v[208:211], v[32:35]
	v_mfma_f32_16x16x32_bf16 v[24:27], v[142:145], v[216:219], v[24:27]
	v_mfma_f32_16x16x32_bf16 v[16:19], v[154:157], v[216:219], v[16:19]
	v_mfma_f32_16x16x32_bf16 v[60:63], v[150:153], v[196:199], v[60:63]
	v_mfma_f32_16x16x32_bf16 v[56:59], v[158:161], v[196:199], v[56:59]
	v_mfma_f32_16x16x32_bf16 v[52:55], v[150:153], v[204:207], v[52:55]
	v_mfma_f32_16x16x32_bf16 v[48:51], v[158:161], v[204:207], v[48:51]
	v_mfma_f32_16x16x32_bf16 v[40:43], v[150:153], v[212:215], v[40:43]
	v_mfma_f32_16x16x32_bf16 v[32:35], v[158:161], v[212:215], v[32:35]
	v_mfma_f32_16x16x32_bf16 v[24:27], v[150:153], v[220:223], v[24:27]
	v_mfma_f32_16x16x32_bf16 v[16:19], v[158:161], v[220:223], v[16:19]
	v_mfma_f32_16x16x32_bf16 v[44:47], v[162:165], v[180:183], v[44:47]
	v_mfma_f32_16x16x32_bf16 v[36:39], v[170:173], v[180:183], v[36:39]
	v_mfma_f32_16x16x32_bf16 v[28:31], v[162:165], v[200:203], v[28:31]
	v_mfma_f32_16x16x32_bf16 v[20:23], v[170:173], v[200:203], v[20:23]
	v_mfma_f32_16x16x32_bf16 v[12:15], v[162:165], v[208:211], v[12:15]
	v_mfma_f32_16x16x32_bf16 v[8:11], v[170:173], v[208:211], v[8:11]
	v_mfma_f32_16x16x32_bf16 v[4:7], v[162:165], v[216:219], v[4:7]
	v_mfma_f32_16x16x32_bf16 v[0:3], v[170:173], v[216:219], v[0:3]
	v_mfma_f32_16x16x32_bf16 v[44:47], v[166:169], v[196:199], v[44:47]
	v_mfma_f32_16x16x32_bf16 v[36:39], v[174:177], v[196:199], v[36:39]
	v_mfma_f32_16x16x32_bf16 v[28:31], v[166:169], v[204:207], v[28:31]
	v_mfma_f32_16x16x32_bf16 v[20:23], v[174:177], v[204:207], v[20:23]
	v_mfma_f32_16x16x32_bf16 v[12:15], v[166:169], v[212:215], v[12:15]
	v_mfma_f32_16x16x32_bf16 v[8:11], v[174:177], v[212:215], v[8:11]
	v_mfma_f32_16x16x32_bf16 v[4:7], v[166:169], v[220:223], v[4:7]
	v_mfma_f32_16x16x32_bf16 v[0:3], v[174:177], v[220:223], v[0:3]
	s_setprio 0
	s_barrier
; #define PG8_STAGE(bufoff, gbase, voff) do { _Pragma("unroll") for (int _i = 0; _i < 2; ++_i) \
;         __builtin_amdgcn_global_load_lds((const unsigned*)((const char*)(gbase) + (voff)[_i]), (PG8_LAS unsigned*)(lds + (bufoff) + ldsw + _i * 8192), 16, 0, 0); } while (0)
; #define PG8_LDA(dst, b, h) do { _Pragma("unroll") for (int m = 0; m < 4; ++m) _Pragma("unroll") for (int k = 0; k < 2; ++k) dst[m][k] = *(const PG8_LAS bf16x8*)(lds + PG8_SA(b, h) + aoff + m * 2048 + k * 1024); } while (0)
; #define PG8_LDB(dst, b, h) do { _Pragma("unroll") for (int n = 0; n < 2; ++n) _Pragma("unroll") for (int k = 0; k < 2; ++k) dst[n][k] = *(const PG8_LAS bf16x8*)(lds + PG8_SB(b, h) + boff + n * 2048 + k * 1024); } while (0)
; #define PG8_MMA(ai, bj, At, Bt) do { __builtin_amdgcn_s_setprio(1); _Pragma("unroll") for (int m = 0; m < 4; ++m) _Pragma("unroll") for (int n = 0; n < 2; ++n) _Pragma("unroll") for (int k = 0; k < 2; ++k) \
;         acc[ai][bj][m][n] = __builtin_amdgcn_mfma_f32_16x16x32_bf16(Bt[n][k], At[m][k], acc[ai][bj][m][n], 0, 0, 0); __builtin_amdgcn_s_setprio(0); } while (0)
; #define PG8_WAIT_V(n) asm volatile("s_waitcnt vmcnt(" #n ")" ::: "memory")
; #define PG8_WAIT_L(n) asm volatile("s_waitcnt lgkmcnt(" #n ")" ::: "memory")
; #define PG8_BAR __builtin_amdgcn_s_barrier()
; #define PG8_SCHED __builtin_amdgcn_sched_barrier(0)
; template <class Epi, class Sched, bool ALIGN_EPI = false, bool SP2 = false>
; __device__ __forceinline__ void gemm_phase(PG8_LAS unsigned char* lds, const Gemm g, const Sched& S, const Epi& E, int wid_s_) {
;     ...
;             PG8_LDB(B0, 1, 0); PG8_LDB(B1, 1, 1); PG8_SCHED; PG8_LDA(At, 1, 0); PG8_STAGE(PG8_SA(0, 1), a2 + hstep, voffA);
;             PG8_WAIT_V(8); PG8_WAIT_L(0); PG8_BAR; PG8_MMA(0, 0, At, B0); PG8_MMA(0, 1, At, B1); PG8_BAR; PG8_SCHED;
;             PG8_LDA(At, 1, 1); PG8_STAGE(PG8_SB(1, 0), b3, voffB); PG8_STAGE(PG8_SB(1, 1), b3 + hstep, voffB); PG8_STAGE(PG8_SA(1, 0), a3, voffA);
;             PG8_WAIT_V(8); PG8_WAIT_L(0); PG8_BAR; PG8_MMA(1, 0, At, B0); PG8_MMA(1, 1, At, B1); PG8_BAR; PG8_SCHED;
	s_add_i32 s78, 16, 0x18000
	v_add_u32_e32 v96, s78, v147
	s_add_i32 s79, 16, 0x1c000
	ds_read_b128 v[142:145], v96
	ds_read_b128 v[150:153], v96 offset:1024
	ds_read_b128 v[154:157], v96 offset:2048
	ds_read_b128 v[158:161], v96 offset:3072
	v_add_u32_e32 v96, s79, v147
	ds_read_b128 v[162:165], v96
	ds_read_b128 v[166:169], v96 offset:1024
	ds_read_b128 v[170:173], v96 offset:2048
	ds_read_b128 v[174:177], v96 offset:3072
	s_mov_b32 m0, s50
	ds_read_b128 v[180:183], v149 offset:32768
	ds_read_b128 v[196:199], v149 offset:33792
	ds_read_b128 v[200:203], v149 offset:34816
	ds_read_b128 v[204:207], v149 offset:35840
	ds_read_b128 v[208:211], v149 offset:36864
	ds_read_b128 v[212:215], v149 offset:37888
	ds_read_b128 v[216:219], v149 offset:38912
	ds_read_b128 v[220:223], v149 offset:39936
	global_load_lds_dwordx4 v188, s[20:21]
	s_mov_b32 m0, s51
	s_nop 0
	global_load_lds_dwordx4 v189, s[20:21]
	s_waitcnt vmcnt(8)
	s_waitcnt lgkmcnt(0)
	s_barrier
	s_setprio 1
	s_waitcnt lgkmcnt(0)
	v_mfma_f32_16x16x32_bf16 v[126:129], v[142:145], v[180:183], v[126:129]
	v_mfma_f32_16x16x32_bf16 v[122:125], v[154:157], v[180:183], v[122:125]
	v_mfma_f32_16x16x32_bf16 v[118:121], v[142:145], v[200:203], v[118:121]
	v_mfma_f32_16x16x32_bf16 v[114:117], v[154:157], v[200:203], v[114:117]
	v_mfma_f32_16x16x32_bf16 v[106:109], v[142:145], v[208:211], v[106:109]
	v_mfma_f32_16x16x32_bf16 v[98:101], v[154:157], v[208:211], v[98:101]
	v_mfma_f32_16x16x32_bf16 v[88:91], v[142:145], v[216:219], v[88:91]
	v_mfma_f32_16x16x32_bf16 v[80:83], v[154:157], v[216:219], v[80:83]
	v_mfma_f32_16x16x32_bf16 v[126:129], v[150:153], v[196:199], v[126:129]
	v_mfma_f32_16x16x32_bf16 v[122:125], v[158:161], v[196:199], v[122:125]
	v_mfma_f32_16x16x32_bf16 v[118:121], v[150:153], v[204:207], v[118:121]
	v_mfma_f32_16x16x32_bf16 v[114:117], v[158:161], v[204:207], v[114:117]
	v_mfma_f32_16x16x32_bf16 v[106:109], v[150:153], v[212:215], v[106:109]
	v_mfma_f32_16x16x32_bf16 v[98:101], v[158:161], v[212:215], v[98:101]
	v_mfma_f32_16x16x32_bf16 v[88:91], v[150:153], v[220:223], v[88:91]
	v_mfma_f32_16x16x32_bf16 v[80:83], v[158:161], v[220:223], v[80:83]
	v_mfma_f32_16x16x32_bf16 v[110:113], v[162:165], v[180:183], v[110:113]
	v_mfma_f32_16x16x32_bf16 v[102:105], v[170:173], v[180:183], v[102:105]
	v_mfma_f32_16x16x32_bf16 v[92:95], v[162:165], v[200:203], v[92:95]
	v_mfma_f32_16x16x32_bf16 v[84:87], v[170:173], v[200:203], v[84:87]
	v_mfma_f32_16x16x32_bf16 v[76:79], v[162:165], v[208:211], v[76:79]
	v_mfma_f32_16x16x32_bf16 v[72:75], v[170:173], v[208:211], v[72:75]
	v_mfma_f32_16x16x32_bf16 v[68:71], v[162:165], v[216:219], v[68:71]
	v_mfma_f32_16x16x32_bf16 v[64:67], v[170:173], v[216:219], v[64:67]
	v_mfma_f32_16x16x32_bf16 v[110:113], v[166:169], v[196:199], v[110:113]
	v_mfma_f32_16x16x32_bf16 v[102:105], v[174:177], v[196:199], v[102:105]
	v_mfma_f32_16x16x32_bf16 v[92:95], v[166:169], v[204:207], v[92:95]
	v_mfma_f32_16x16x32_bf16 v[84:87], v[174:177], v[204:207], v[84:87]
	v_mfma_f32_16x16x32_bf16 v[76:79], v[166:169], v[212:215], v[76:79]
	v_mfma_f32_16x16x32_bf16 v[72:75], v[174:177], v[212:215], v[72:75]
	v_mfma_f32_16x16x32_bf16 v[68:71], v[166:169], v[220:223], v[68:71]
	v_mfma_f32_16x16x32_bf16 v[64:67], v[174:177], v[220:223], v[64:67]
	s_setprio 0
	s_barrier
	s_add_i32 m0, s78, s41
	ds_read_b128 v[180:183], v149 offset:49152
	ds_read_b128 v[196:199], v149 offset:50176
	ds_read_b128 v[200:203], v149 offset:51200
	ds_read_b128 v[204:207], v149 offset:52224
	ds_read_b128 v[208:211], v149 offset:53248
	ds_read_b128 v[212:215], v149 offset:54272
	ds_read_b128 v[216:219], v149 offset:55296
	ds_read_b128 v[220:223], v149 offset:56320
	global_load_lds_dwordx4 v194, s[8:9]
	s_add_i32 m0, s78, s41
	s_addk_i32 m0, 0x2000
	s_nop 0
	global_load_lds_dwordx4 v195, s[8:9]
	s_add_i32 m0, s79, s41
	s_nop 0
	global_load_lds_dwordx4 v224, s[8:9]
	s_add_i32 m0, s79, s41
	s_addk_i32 m0, 0x2000
	s_nop 0
	global_load_lds_dwordx4 v225, s[8:9]
	s_mov_b32 m0, s80
	s_nop 0
	global_load_lds_dwordx4 v226, s[20:21]
	s_mov_b32 m0, s81
	s_nop 0
	global_load_lds_dwordx4 v227, s[20:21]
	s_waitcnt vmcnt(8)
	s_waitcnt lgkmcnt(0)
	s_barrier
; #define PG8_STAGE(bufoff, gbase, voff) do { _Pragma("unroll") for (int _i = 0; _i < 2; ++_i) \
;         __builtin_amdgcn_global_load_lds((const unsigned*)((const char*)(gbase) + (voff)[_i]), (PG8_LAS unsigned*)(lds + (bufoff) + ldsw + _i * 8192), 16, 0, 0); } while (0)
; #define PG8_LDA(dst, b, h) do { _Pragma("unroll") for (int m = 0; m < 4; ++m) _Pragma("unroll") for (int k = 0; k < 2; ++k) dst[m][k] = *(const PG8_LAS bf16x8*)(lds + PG8_SA(b, h) + aoff + m * 2048 + k * 1024); } while (0)
; #define PG8_MMA(ai, bj, At, Bt) do { __builtin_amdgcn_s_setprio(1); _Pragma("unroll") for (int m = 0; m < 4; ++m) _Pragma("unroll") for (int n = 0; n < 2; ++n) _Pragma("unroll") for (int k = 0; k < 2; ++k) \
;         acc[ai][bj][m][n] = __builtin_amdgcn_mfma_f32_16x16x32_bf16(Bt[n][k], At[m][k], acc[ai][bj][m][n], 0, 0, 0); __builtin_amdgcn_s_setprio(0); } while (0)
; #define PG8_WAIT_V(n) asm volatile("s_waitcnt vmcnt(" #n ")" ::: "memory")
; #define PG8_WAIT_L(n) asm volatile("s_waitcnt lgkmcnt(" #n ")" ::: "memory")
; #define PG8_BAR __builtin_amdgcn_s_barrier()
; #define PG8_SCHED __builtin_amdgcn_sched_barrier(0)
; template <class Epi, class Sched, bool ALIGN_EPI = false, bool SP2 = false>
; __device__ __forceinline__ void gemm_phase(PG8_LAS unsigned char* lds, const Gemm g, const Sched& S, const Epi& E, int wid_s_) {
;     ...
;             PG8_WAIT_V(8); PG8_WAIT_L(0); PG8_BAR; PG8_MMA(0, 0, At, B0); PG8_MMA(0, 1, At, B1); PG8_BAR; PG8_SCHED;
;             PG8_LDA(At, 1, 1); PG8_STAGE(PG8_SB(1, 0), b3, voffB); PG8_STAGE(PG8_SB(1, 1), b3 + hstep, voffB); PG8_STAGE(PG8_SA(1, 0), a3, voffA);
;             PG8_WAIT_V(8); PG8_WAIT_L(0); PG8_BAR; PG8_MMA(1, 0, At, B0); PG8_MMA(1, 1, At, B1); PG8_BAR; PG8_SCHED;
;     __device__ __forceinline__ void operator()(const f32x4 (&acc)[2][2][4][2], const Unit& u, int wr, int wc, int fr, int fq) const {
;     ...
;                 for (int bj = 0; bj < 2; ++bj) { const int n = col0 + bj * HALF, half = n >> 10;
;                     const f32x4 v0 = acc[ai][bj][m][0] * scale, v1 = acc[ai][bj][m][1] * scale;
;                     u32x4 w; w.x = cvtpk(v0[0], v0[1]); w.y = cvtpk(v0[2], v0[3]); w.z = cvtpk(v1[0], v1[1]); w.w = cvtpk(v1[2], v1[3]);
;                     *(u32x4*)(O + ((size_t)(jg * 2 + half) * 512 + d) * 1024 + (n & 1023)) = w; } }
	s_setprio 1
	s_waitcnt lgkmcnt(0)
	v_mfma_f32_16x16x32_bf16 v[60:63], v[142:145], v[180:183], v[60:63]
	v_mfma_f32_16x16x32_bf16 v[56:59], v[154:157], v[180:183], v[56:59]
	v_mfma_f32_16x16x32_bf16 v[52:55], v[142:145], v[200:203], v[52:55]
	v_mfma_f32_16x16x32_bf16 v[48:51], v[154:157], v[200:203], v[48:51]
	v_mfma_f32_16x16x32_bf16 v[40:43], v[142:145], v[208:211], v[40:43]
	v_mfma_f32_16x16x32_bf16 v[32:35], v[154:157], v[208:211], v[32:35]
	v_mfma_f32_16x16x32_bf16 v[24:27], v[142:145], v[216:219], v[24:27]
	v_mfma_f32_16x16x32_bf16 v[16:19], v[154:157], v[216:219], v[16:19]
	v_mfma_f32_16x16x32_bf16 v[60:63], v[150:153], v[196:199], v[60:63]
	v_mfma_f32_16x16x32_bf16 v[56:59], v[158:161], v[196:199], v[56:59]
	v_mfma_f32_16x16x32_bf16 v[52:55], v[150:153], v[204:207], v[52:55]
	v_mfma_f32_16x16x32_bf16 v[48:51], v[158:161], v[204:207], v[48:51]
	v_mfma_f32_16x16x32_bf16 v[40:43], v[150:153], v[212:215], v[40:43]
	v_mfma_f32_16x16x32_bf16 v[32:35], v[158:161], v[212:215], v[32:35]
	v_mfma_f32_16x16x32_bf16 v[24:27], v[150:153], v[220:223], v[24:27]
	v_mfma_f32_16x16x32_bf16 v[16:19], v[158:161], v[220:223], v[16:19]
	v_mfma_f32_16x16x32_bf16 v[44:47], v[162:165], v[180:183], v[44:47]
	v_mfma_f32_16x16x32_bf16 v[36:39], v[170:173], v[180:183], v[36:39]
	v_mfma_f32_16x16x32_bf16 v[28:31], v[162:165], v[200:203], v[28:31]
	v_mfma_f32_16x16x32_bf16 v[20:23], v[170:173], v[200:203], v[20:23]
	v_mfma_f32_16x16x32_bf16 v[12:15], v[162:165], v[208:211], v[12:15]
	v_mfma_f32_16x16x32_bf16 v[8:11], v[170:173], v[208:211], v[8:11]
	v_mfma_f32_16x16x32_bf16 v[4:7], v[162:165], v[216:219], v[4:7]
	v_mfma_f32_16x16x32_bf16 v[0:3], v[170:173], v[216:219], v[0:3]
	v_mfma_f32_16x16x32_bf16 v[44:47], v[166:169], v[196:199], v[44:47]
	v_mfma_f32_16x16x32_bf16 v[36:39], v[174:177], v[196:199], v[36:39]
	v_mfma_f32_16x16x32_bf16 v[28:31], v[166:169], v[204:207], v[28:31]
	v_mfma_f32_16x16x32_bf16 v[20:23], v[174:177], v[204:207], v[20:23]
	v_mfma_f32_16x16x32_bf16 v[12:15], v[166:169], v[212:215], v[12:15]
	v_mfma_f32_16x16x32_bf16 v[8:11], v[174:177], v[212:215], v[8:11]
	v_mfma_f32_16x16x32_bf16 v[4:7], v[166:169], v[220:223], v[4:7]
	v_mfma_f32_16x16x32_bf16 v[0:3], v[174:177], v[220:223], v[0:3]
	s_setprio 0
	s_barrier
	s_add_u32 s91, s91, 0x100
	s_addc_u32 vcc_lo, vcc_lo, 0
	s_add_u32 s18, s18, 0x100
	s_addc_u32 s19, s19, 0
	s_cmp_ge_i32 vcc_hi, s82
	s_mov_b32 s20, vcc_hi
	s_cbranch_scc0 .LBB0_788
	s_add_i32 s8, s79, s41
	s_mov_b32 s8, 0x39b504f3
	v_pk_mul_f32 v[128:129], v[128:129], s[8:9] op_sel_hi:[1,0]
	v_pk_mul_f32 v[126:127], v[126:127], s[8:9] op_sel_hi:[1,0]
	v_pk_mul_f32 v[124:125], v[124:125], s[8:9] op_sel_hi:[1,0]
	v_pk_mul_f32 v[122:123], v[122:123], s[8:9] op_sel_hi:[1,0]
	v_pk_mul_f32 v[142:143], v[112:113], s[8:9] op_sel_hi:[1,0]
	v_pk_mul_f32 v[144:145], v[110:111], s[8:9] op_sel_hi:[1,0]
	v_pk_mul_f32 v[152:153], v[104:105], s[8:9] op_sel_hi:[1,0]
	v_pk_mul_f32 v[154:155], v[102:103], s[8:9] op_sel_hi:[1,0]
	v_pk_mul_f32 v[102:103], v[120:121], s[8:9] op_sel_hi:[1,0]
	v_pk_mul_f32 v[104:105], v[118:119], s[8:9] op_sel_hi:[1,0]
	v_pk_mul_f32 v[110:111], v[116:117], s[8:9] op_sel_hi:[1,0]
	v_pk_mul_f32 v[112:113], v[114:115], s[8:9] op_sel_hi:[1,0]
	v_pk_mul_f32 v[114:115], v[94:95], s[8:9] op_sel_hi:[1,0]
	v_pk_mul_f32 v[116:117], v[92:93], s[8:9] op_sel_hi:[1,0]
	v_pk_mul_f32 v[118:119], v[86:87], s[8:9] op_sel_hi:[1,0]
	v_pk_mul_f32 v[120:121], v[84:85], s[8:9] op_sel_hi:[1,0]
	v_pk_mul_f32 v[84:85], v[108:109], s[8:9] op_sel_hi:[1,0]
	v_pk_mul_f32 v[86:87], v[106:107], s[8:9] op_sel_hi:[1,0]
	v_pk_mul_f32 v[92:93], v[100:101], s[8:9] op_sel_hi:[1,0]
	v_pk_mul_f32 v[94:95], v[98:99], s[8:9] op_sel_hi:[1,0]
	v_pk_mul_f32 v[98:99], v[78:79], s[8:9] op_sel_hi:[1,0]
	v_pk_mul_f32 v[100:101], v[76:77], s[8:9] op_sel_hi:[1,0]
	v_pk_mul_f32 v[106:107], v[74:75], s[8:9] op_sel_hi:[1,0]
	v_pk_mul_f32 v[108:109], v[72:73], s[8:9] op_sel_hi:[1,0]
	v_pk_mul_f32 v[72:73], v[90:91], s[8:9] op_sel_hi:[1,0]
	v_pk_mul_f32 v[74:75], v[88:89], s[8:9] op_sel_hi:[1,0]
	v_pk_mul_f32 v[76:77], v[82:83], s[8:9] op_sel_hi:[1,0]
	v_pk_mul_f32 v[78:79], v[80:81], s[8:9] op_sel_hi:[1,0]
	v_pk_mul_f32 v[70:71], v[70:71], s[8:9] op_sel_hi:[1,0]
	v_pk_mul_f32 v[68:69], v[68:69], s[8:9] op_sel_hi:[1,0]
	v_pk_mul_f32 v[66:67], v[66:67], s[8:9] op_sel_hi:[1,0]
	v_pk_mul_f32 v[64:65], v[64:65], s[8:9] op_sel_hi:[1,0]
	v_pk_mul_f32 v[62:63], v[62:63], s[8:9] op_sel_hi:[1,0]
	v_pk_mul_f32 v[60:61], v[60:61], s[8:9] op_sel_hi:[1,0]
	v_pk_mul_f32 v[58:59], v[58:59], s[8:9] op_sel_hi:[1,0]
	v_pk_mul_f32 v[56:57], v[56:57], s[8:9] op_sel_hi:[1,0]
	v_pk_mul_f32 v[80:81], v[46:47], s[8:9] op_sel_hi:[1,0]
	v_pk_mul_f32 v[82:83], v[44:45], s[8:9] op_sel_hi:[1,0]
	v_pk_mul_f32 v[88:89], v[38:39], s[8:9] op_sel_hi:[1,0]
	v_pk_mul_f32 v[90:91], v[36:37], s[8:9] op_sel_hi:[1,0]
	v_pk_mul_f32 v[36:37], v[54:55], s[8:9] op_sel_hi:[1,0]
	v_pk_mul_f32 v[38:39], v[52:53], s[8:9] op_sel_hi:[1,0]
	v_pk_mul_f32 v[44:45], v[50:51], s[8:9] op_sel_hi:[1,0]
	v_pk_mul_f32 v[46:47], v[48:49], s[8:9] op_sel_hi:[1,0]
	v_pk_mul_f32 v[48:49], v[30:31], s[8:9] op_sel_hi:[1,0]
	v_pk_mul_f32 v[50:51], v[28:29], s[8:9] op_sel_hi:[1,0]
	v_pk_mul_f32 v[52:53], v[22:23], s[8:9] op_sel_hi:[1,0]
	v_pk_mul_f32 v[54:55], v[20:21], s[8:9] op_sel_hi:[1,0]
	v_pk_mul_f32 v[20:21], v[42:43], s[8:9] op_sel_hi:[1,0]
	v_pk_mul_f32 v[22:23], v[40:41], s[8:9] op_sel_hi:[1,0]
	v_pk_mul_f32 v[28:29], v[34:35], s[8:9] op_sel_hi:[1,0]
	v_pk_mul_f32 v[30:31], v[32:33], s[8:9] op_sel_hi:[1,0]
	v_pk_mul_f32 v[32:33], v[14:15], s[8:9] op_sel_hi:[1,0]
	v_pk_mul_f32 v[34:35], v[12:13], s[8:9] op_sel_hi:[1,0]
	v_pk_mul_f32 v[40:41], v[10:11], s[8:9] op_sel_hi:[1,0]
	v_pk_mul_f32 v[42:43], v[8:9], s[8:9] op_sel_hi:[1,0]
	v_pk_mul_f32 v[8:9], v[26:27], s[8:9] op_sel_hi:[1,0]
	v_pk_mul_f32 v[10:11], v[24:25], s[8:9] op_sel_hi:[1,0]
	v_pk_mul_f32 v[12:13], v[18:19], s[8:9] op_sel_hi:[1,0]
	v_pk_mul_f32 v[14:15], v[16:17], s[8:9] op_sel_hi:[1,0]
	v_pk_mul_f32 v[6:7], v[6:7], s[8:9] op_sel_hi:[1,0]
	v_pk_mul_f32 v[4:5], v[4:5], s[8:9] op_sel_hi:[1,0]
	v_pk_mul_f32 v[2:3], v[2:3], s[8:9] op_sel_hi:[1,0]
	v_pk_mul_f32 v[0:1], v[0:1], s[8:9] op_sel_hi:[1,0]
